# natten: query waits no longer wait for the previous row's output stores (per-half counted vmcnt), on v024
# baseline (speedup 1.0000x reference)
.LBB0_814:
	v_med3_u32 v24, s12, 4, 28
	v_med3_u32 v25, s12, 3, 27
	s_cmp_lg_u32 s13, 1
	v_add_u32_e32 v26, -1, v24
	s_cselect_b64 s[58:59], -1, 0
	v_cmp_ne_u32_e32 vcc, v25, v26
	s_and_b64 s[34:35], s[58:59], vcc
	v_cndmask_b32_e64 v25, 0, 1, s[34:35]
	v_cmp_ne_u32_e64 s[10:11], 1, v25
	v_readfirstlane_b32 s83, v24
	s_cmp_lt_u32 s91, 4
	s_cselect_b32 s87, 4, 0
	s_cmp_eq_u32 s12, 0
	s_cselect_b32 s87, 0, s87
	s_cmp_eq_u32 s87, 0
	s_cbranch_scc1 .Lmy_q1s
	s_waitcnt vmcnt(5)
	s_branch .Lmy_q1d

.Lmy_q1d:
	v_lshlrev_b32_e32 v46, 16, v0
	v_and_b32_e32 v47, 0xffff0000, v0
	v_lshlrev_b32_e32 v42, 16, v1
	v_and_b32_e32 v43, 0xffff0000, v1
	v_pk_mul_f32 v[62:63], v[46:47], v[46:47]
	v_pk_mul_f32 v[58:59], v[42:43], v[42:43]
	v_add_f32_e32 v62, v62, v63
	v_lshlrev_b32_e32 v38, 16, v2
	v_and_b32_e32 v39, 0xffff0000, v2
	v_add_f32_e32 v58, v58, v62
	v_pk_mul_f32 v[54:55], v[38:39], v[38:39]
	v_add_f32_e32 v58, v59, v58
	v_lshlrev_b32_e32 v34, 16, v3
	v_and_b32_e32 v35, 0xffff0000, v3
	v_add_f32_e32 v54, v54, v58
	v_pk_mul_f32 v[50:51], v[34:35], v[34:35]
	v_add_f32_e32 v54, v55, v54
	s_cmp_eq_u32 s87, 0
	s_cbranch_scc1 .Lmy_q2s
	s_waitcnt vmcnt(4)
	s_branch .Lmy_q2d

.Lmy_q2d:
	s_and_b64 vcc, exec, s[10:11]
	s_cbranch_vccnz .Lmy_noslide
	s_add_i32 s86, s83, 4
	s_mul_i32 s88, s86, 0x30000
	s_mov_b32 s89, 0
	v_lshl_add_u64 v[24:25], s[88:89], 1, v[84:85]
	v_lshl_add_u64 v[26:27], v[24:25], 0, s[54:55]
	global_load_dwordx4 v[28:31], v[24:25], off offset:2048
	s_nop 0
	global_load_dwordx4 v[24:27], v[26:27], off offset:2048
	v_mov_b32_e32 v79, 0x358637bd
	s_and_saveexec_b64 s[98:99], s[6:7]
	s_cbranch_execz .Lmy_s817
	s_lshl_b32 s88, s86, 6
	v_lshl_add_u64 v[222:223], s[88:89], 2, v[86:87]
	v_add_co_u32_e32 v224, vcc, 0x20000, v222
	s_nop 1
	v_addc_co_u32_e32 v225, vcc, 0, v223, vcc
	global_load_dword v226, v[222:223], off
	s_nop 0
	global_load_dword v227, v[224:225], off
